# stack7 plus general GEMM K-loop head reordered: first A-fragment ds_reads issue before the scalar select block
# baseline (speedup 1.0000x reference)
; #define PG8_STAGE(bufoff, gbase, v0, dv) do { _Pragma("unroll") for (int _i = 0; _i < 2; ++_i) \
;         __builtin_amdgcn_global_load_lds((const unsigned*)((const char*)(gbase) + ((v0) + (unsigned)_i * (dv))), (PG8_LAS unsigned*)(lds + (bufoff) + ldsw + _i * 8192), 16, 0, 0); } while (0)
; #define PG8_LDA(dst, b, h) do { _Pragma("unroll") for (int m = 0; m < 4; ++m) _Pragma("unroll") for (int k = 0; k < 2; ++k) dst[m][k] = *(const PG8_LAS bf16x8*)(lds + PG8_SA(b, h) + aoff + m * 2048 + k * 1024); } while (0)
; #define PG8_LDB(dst, b, h) do { _Pragma("unroll") for (int n = 0; n < 2; ++n) _Pragma("unroll") for (int k = 0; k < 2; ++k) dst[n][k] = *(const PG8_LAS bf16x8*)(lds + PG8_SB(b, h) + boff + n * 2048 + k * 1024); } while (0)
; #define PG8_MMA(ai, bj, At, Bt) do { __builtin_amdgcn_s_setprio(1); _Pragma("unroll") for (int m = 0; m < 4; ++m) _Pragma("unroll") for (int n = 0; n < 2; ++n) _Pragma("unroll") for (int k = 0; k < 2; ++k) \
;         acc[ai][bj][m][n] = __builtin_amdgcn_mfma_f32_16x16x32_bf16(Bt[n][k], At[m][k], acc[ai][bj][m][n], 0, 0, 0); __builtin_amdgcn_s_setprio(0); } while (0)
; template <class Epi, class Sched, bool MERGE>
; __device__ __forceinline__ void gemm_stream(PG8_LAS unsigned char* lds, const Sched& S, const Epi& E) {
;     ...
;         const int nt = cur.K / BK; const unsigned ck2 = (unsigned)(2 * cur.K), nk2 = (unsigned)(2 * nxt.K);
;         for (int t = 0; t < nt; t += 2) {
;             const bool last = (t == nt - 2);
;             const char* a1 = cA + (size_t)(t + 1) * kstep;
;             const char* a2 = last ? nA : cA + (size_t)(t + 2) * kstep; const char* b2 = last ? nB : cB + (size_t)(t + 2) * kstep;
;             const char* a3 = a2 + kstep; const char* b3 = b2 + kstep;
;             const size_t hs2 = last ? nhs : chs;
;             const unsigned k2b = last ? nk2 : ck2;
;             const unsigned cvA = rA0 * ck2 + c20, cdv = 64u * ck2, vA2 = rA0 * k2b + c20, vB2 = rB0 * k2b + c20, dv2 = 64u * k2b;
;             PG8_LDB(B0, 0, 0); PG8_LDB(B1, 0, 1); PG8_SCHED; PG8_LDA(At, 0, 0); PG8_STAGE(PG8_SA(1, 1), a1 + chs, cvA, cdv);
;             PG8_WAIT_V(8); PG8_WAIT_L(0); PG8_BAR; PG8_MMA(0, 0, At, B0); PG8_MMA(0, 1, At, B1); PG8_BAR; PG8_SCHED;
;             PG8_LDA(At, 0, 1); PG8_STAGE(PG8_SB(0, 0), b2, vB2, dv2); PG8_STAGE(PG8_SB(0, 1), b2 + hs2, vB2, dv2); PG8_STAGE(PG8_SA(0, 0), a2, vA2, dv2);
.LBB0_235:
	s_ashr_i32 s27, s26, 31
	s_lshl_b64 s[28:29], s[26:27], 8
	v_mov_b32_e32 v127, 0
	s_cmp_lt_i32 s61, 64
	s_cbranch_scc1 .LBB0_238
	s_ashr_i32 s6, s61, 31
	s_lshr_b32 s6, s6, 26
	s_add_i32 s6, s61, s6
	s_ashr_i32 s27, s6, 6
	s_lshl_b32 s46, s61, 1
	s_lshl_b32 s47, s26, 1
	s_add_i32 s59, s27, -2
	s_add_u32 s6, s34, 0x80
	s_addc_u32 s7, s35, 0
	v_mad_u64_u32 v[0:1], s[34:35], s46, v137, v[144:145]
	v_mov_b32_e32 v1, v179
	v_lshl_add_u64 v[128:129], s[30:31], 0, v[0:1]
	v_mad_u64_u32 v[0:1], s[34:35], v164, s61, v[144:145]
	v_mov_b32_e32 v1, v179
	s_add_u32 s73, s36, 0x100
	v_lshl_add_u64 v[130:131], s[30:31], 0, v[0:1]
	s_addc_u32 s94, s37, 0
	s_mov_b32 vcc_lo, 0
	s_mov_b32 s96, 0x10000
	v_add_u32_e32 v154, s96, v162
	v_add_u32_e32 v175, 0x14000, v162
	ds_read_b128 v[132:135], v154
	ds_read_b128 v[146:149], v154 offset:1024
	ds_read_b128 v[150:153], v154 offset:2048
	ds_read_b128 v[154:157], v154 offset:3072
	ds_read_b128 v[158:161], v175
	ds_read_b128 v[166:169], v175 offset:1024
	ds_read_b128 v[170:173], v175 offset:2048
	ds_read_b128 v[180:183], v175 offset:3072
	s_cmp_eq_u32 s59, vcc_lo
	s_cselect_b64 s[36:37], -1, 0
	s_add_i32 vcc_lo, vcc_lo, 2
	s_add_u32 s50, s6, 0x80
	s_addc_u32 s51, s7, 0
	s_and_b64 s[34:35], s[36:37], exec
	s_cselect_b32 s35, s23, s51
	s_cselect_b32 s34, s22, s50
	s_cselect_b32 s58, s47, s46
	s_cselect_b32 s61, s29, s31
	s_cselect_b32 vcc_hi, s28, s30
	s_add_i32 s96, 0, 0x10000
	v_mad_u64_u32 v[174:175], s[50:51], s58, v139, v[136:137]
	s_and_b64 s[36:37], s[36:37], exec
	v_mad_u64_u32 v[224:225], s[50:51], s58, v137, v[136:137]
	s_cselect_b32 s37, s25, s94
	s_cselect_b32 s36, s24, s73
	s_add_i32 s50, 0, 0x14000
	v_lshl_add_u64 v[230:231], s[6:7], 0, v[128:129]
	s_add_i32 m0, s66, 0xc000
	ds_read_b128 v[192:195], v165
	ds_read_b128 v[196:199], v165 offset:1024
	ds_read_b128 v[200:203], v165 offset:2048
	ds_read_b128 v[204:207], v165 offset:3072
	ds_read_b128 v[208:211], v165 offset:4096
	ds_read_b128 v[212:215], v165 offset:5120
	ds_read_b128 v[216:219], v165 offset:6144
	ds_read_b128 v[220:223], v165 offset:7168
	global_load_lds_dwordx4 v[230:231], off
	v_lshl_add_u64 v[230:231], s[6:7], 0, v[130:131]
	s_add_i32 m0, s66, 0xe000
	s_nop 0
	global_load_lds_dwordx4 v[230:231], off
	s_waitcnt vmcnt(8)
	s_waitcnt lgkmcnt(0)
	s_barrier
	s_setprio 1
	s_waitcnt lgkmcnt(0)
	v_mfma_f32_16x16x32_bf16 v[124:127], v[132:135], v[192:195], 0
	v_mfma_f32_16x16x32_bf16 v[120:123], v[150:153], v[192:195], 0
	v_mfma_f32_16x16x32_bf16 v[108:111], v[132:135], v[200:203], 0
	v_mfma_f32_16x16x32_bf16 v[104:107], v[150:153], v[200:203], 0
	v_mfma_f32_16x16x32_bf16 v[92:95], v[132:135], v[208:211], 0
	v_mfma_f32_16x16x32_bf16 v[88:91], v[150:153], v[208:211], 0
	v_mfma_f32_16x16x32_bf16 v[76:79], v[132:135], v[216:219], 0
	v_mfma_f32_16x16x32_bf16 v[72:75], v[150:153], v[216:219], 0
	v_mfma_f32_16x16x32_bf16 v[124:127], v[146:149], v[196:199], v[124:127]
	v_mfma_f32_16x16x32_bf16 v[120:123], v[154:157], v[196:199], v[120:123]
	v_mfma_f32_16x16x32_bf16 v[108:111], v[146:149], v[204:207], v[108:111]
	v_mfma_f32_16x16x32_bf16 v[104:107], v[154:157], v[204:207], v[104:107]
	v_mfma_f32_16x16x32_bf16 v[92:95], v[146:149], v[212:215], v[92:95]
	v_mfma_f32_16x16x32_bf16 v[88:91], v[154:157], v[212:215], v[88:91]
	v_mfma_f32_16x16x32_bf16 v[76:79], v[146:149], v[220:223], v[76:79]
	v_mfma_f32_16x16x32_bf16 v[72:75], v[154:157], v[220:223], v[72:75]
	s_setprio 0
	s_setprio 1
	v_mfma_f32_16x16x32_bf16 v[116:119], v[158:161], v[192:195], 0
	v_mfma_f32_16x16x32_bf16 v[112:115], v[170:173], v[192:195], 0
	v_mfma_f32_16x16x32_bf16 v[100:103], v[158:161], v[200:203], 0
	v_mfma_f32_16x16x32_bf16 v[96:99], v[170:173], v[200:203], 0
	v_mfma_f32_16x16x32_bf16 v[84:87], v[158:161], v[208:211], 0
	v_mfma_f32_16x16x32_bf16 v[80:83], v[170:173], v[208:211], 0
	v_mfma_f32_16x16x32_bf16 v[68:71], v[158:161], v[216:219], 0
	v_mfma_f32_16x16x32_bf16 v[64:67], v[170:173], v[216:219], 0
	v_mfma_f32_16x16x32_bf16 v[116:119], v[166:169], v[196:199], v[116:119]
	v_mfma_f32_16x16x32_bf16 v[112:115], v[180:183], v[196:199], v[112:115]
	v_mfma_f32_16x16x32_bf16 v[100:103], v[166:169], v[204:207], v[100:103]
	v_mfma_f32_16x16x32_bf16 v[96:99], v[180:183], v[204:207], v[96:99]
	v_mfma_f32_16x16x32_bf16 v[84:87], v[166:169], v[212:215], v[84:87]
	v_mfma_f32_16x16x32_bf16 v[80:83], v[180:183], v[212:215], v[80:83]
	v_mfma_f32_16x16x32_bf16 v[68:71], v[166:169], v[220:223], v[68:71]
	v_mfma_f32_16x16x32_bf16 v[64:67], v[180:183], v[220:223], v[64:67]
	s_setprio 0
	s_barrier
	s_lshl_b32 s51, s58, 6
	s_add_i32 s58, s96, s65
	s_mov_b32 m0, s58
	ds_read_b128 v[192:195], v165 offset:16384
	ds_read_b128 v[196:199], v165 offset:17408
	ds_read_b128 v[200:203], v165 offset:18432
	ds_read_b128 v[204:207], v165 offset:19456
	ds_read_b128 v[208:211], v165 offset:20480
	ds_read_b128 v[212:215], v165 offset:21504
	ds_read_b128 v[216:219], v165 offset:22528
	ds_read_b128 v[220:223], v165 offset:23552
	v_mov_b32_e32 v175, v179
	global_load_lds_dwordx4 v174, s[36:37]
	v_add_u32_e32 v178, s51, v174
	s_add_i32 m0, s58, 0x2000
	v_lshl_add_u64 v[230:231], s[36:37], 0, v[174:175]
	v_lshl_add_u64 v[232:233], s[36:37], 0, v[178:179]
	global_load_lds_dwordx4 v178, s[36:37]
	s_add_u32 s36, s36, vcc_hi
	s_addc_u32 s37, s37, s61
	s_add_i32 s50, s50, s65
	s_mov_b32 m0, s50
	v_lshl_add_u64 v[234:235], s[36:37], 0, v[174:175]
	global_load_lds_dwordx4 v174, s[36:37]
	s_add_i32 m0, s50, 0x2000
	v_lshl_add_u64 v[174:175], s[36:37], 0, v[178:179]
	global_load_lds_dwordx4 v178, s[36:37]
	s_mov_b32 m0, s66
	v_add_u32_e32 v178, s51, v224
	global_load_lds_dwordx4 v224, s[34:35]
	s_mov_b32 m0, s67
	v_mov_b32_e32 v225, v179
	global_load_lds_dwordx4 v178, s[34:35]
	s_waitcnt vmcnt(8)
	s_waitcnt lgkmcnt(0)
	v_lshl_add_u64 v[236:237], s[34:35], 0, v[224:225]
	v_lshl_add_u64 v[238:239], s[34:35], 0, v[178:179]
	s_barrier
; #define PG8_STAGE(bufoff, gbase, v0, dv) do { _Pragma("unroll") for (int _i = 0; _i < 2; ++_i) \
;         __builtin_amdgcn_global_load_lds((const unsigned*)((const char*)(gbase) + ((v0) + (unsigned)_i * (dv))), (PG8_LAS unsigned*)(lds + (bufoff) + ldsw + _i * 8192), 16, 0, 0); } while (0)
; #define PG8_LDA(dst, b, h) do { _Pragma("unroll") for (int m = 0; m < 4; ++m) _Pragma("unroll") for (int k = 0; k < 2; ++k) dst[m][k] = *(const PG8_LAS bf16x8*)(lds + PG8_SA(b, h) + aoff + m * 2048 + k * 1024); } while (0)
; #define PG8_LDB(dst, b, h) do { _Pragma("unroll") for (int n = 0; n < 2; ++n) _Pragma("unroll") for (int k = 0; k < 2; ++k) dst[n][k] = *(const PG8_LAS bf16x8*)(lds + PG8_SB(b, h) + boff + n * 2048 + k * 1024); } while (0)
; #define PG8_MMA(ai, bj, At, Bt) do { __builtin_amdgcn_s_setprio(1); _Pragma("unroll") for (int m = 0; m < 4; ++m) _Pragma("unroll") for (int n = 0; n < 2; ++n) _Pragma("unroll") for (int k = 0; k < 2; ++k) \
;         acc[ai][bj][m][n] = __builtin_amdgcn_mfma_f32_16x16x32_bf16(Bt[n][k], At[m][k], acc[ai][bj][m][n], 0, 0, 0); __builtin_amdgcn_s_setprio(0); } while (0)
; #define PG8_WAIT_V(n) asm volatile("s_waitcnt vmcnt(" #n ")" ::: "memory")
; #define PG8_WAIT_L(n) asm volatile("s_waitcnt lgkmcnt(" #n ")" ::: "memory")
; #define PG8_BAR __builtin_amdgcn_s_barrier()
; #define PG8_SCHED __builtin_amdgcn_sched_barrier(0)
; template <class Epi, class Sched, bool MERGE>
; __device__ __forceinline__ void gemm_stream(PG8_LAS unsigned char* lds, const Sched& S, const Epi& E) {
;     ...
;             PG8_WAIT_V(8); PG8_WAIT_L(0); PG8_BAR; PG8_MMA(1, 0, At, B0); PG8_MMA(1, 1, At, B1); PG8_BAR; PG8_SCHED;
;             PG8_LDB(B0, 1, 0); PG8_LDB(B1, 1, 1); PG8_SCHED; PG8_LDA(At, 1, 0); PG8_STAGE(PG8_SA(0, 1), a2 + hs2, vA2, dv2);
;             PG8_WAIT_V(8); PG8_WAIT_L(0); PG8_BAR; PG8_MMA(0, 0, At, B0); PG8_MMA(0, 1, At, B1); PG8_BAR; PG8_SCHED;
	s_setprio 1
	s_waitcnt lgkmcnt(0)
	v_mfma_f32_16x16x32_bf16 v[60:63], v[132:135], v[192:195], 0
	v_mfma_f32_16x16x32_bf16 v[56:59], v[150:153], v[192:195], 0
	v_mfma_f32_16x16x32_bf16 v[44:47], v[132:135], v[200:203], 0
	v_mfma_f32_16x16x32_bf16 v[40:43], v[150:153], v[200:203], 0
	v_mfma_f32_16x16x32_bf16 v[28:31], v[132:135], v[208:211], 0
	v_mfma_f32_16x16x32_bf16 v[24:27], v[150:153], v[208:211], 0
	v_mfma_f32_16x16x32_bf16 v[12:15], v[132:135], v[216:219], 0
	v_mfma_f32_16x16x32_bf16 v[8:11], v[150:153], v[216:219], 0
	v_mfma_f32_16x16x32_bf16 v[60:63], v[146:149], v[196:199], v[60:63]
	v_mfma_f32_16x16x32_bf16 v[56:59], v[154:157], v[196:199], v[56:59]
	v_mfma_f32_16x16x32_bf16 v[44:47], v[146:149], v[204:207], v[44:47]
	v_mfma_f32_16x16x32_bf16 v[40:43], v[154:157], v[204:207], v[40:43]
	v_mfma_f32_16x16x32_bf16 v[28:31], v[146:149], v[212:215], v[28:31]
	v_mfma_f32_16x16x32_bf16 v[24:27], v[154:157], v[212:215], v[24:27]
	v_mfma_f32_16x16x32_bf16 v[12:15], v[146:149], v[220:223], v[12:15]
	v_mfma_f32_16x16x32_bf16 v[8:11], v[154:157], v[220:223], v[8:11]
	s_setprio 0
	s_setprio 1
	v_mfma_f32_16x16x32_bf16 v[52:55], v[158:161], v[192:195], 0
	v_mfma_f32_16x16x32_bf16 v[48:51], v[170:173], v[192:195], 0
	v_mfma_f32_16x16x32_bf16 v[36:39], v[158:161], v[200:203], 0
	v_mfma_f32_16x16x32_bf16 v[32:35], v[170:173], v[200:203], 0
	v_mfma_f32_16x16x32_bf16 v[20:23], v[158:161], v[208:211], 0
	v_mfma_f32_16x16x32_bf16 v[16:19], v[170:173], v[208:211], 0
	v_mfma_f32_16x16x32_bf16 v[4:7], v[158:161], v[216:219], 0
	v_mfma_f32_16x16x32_bf16 v[0:3], v[170:173], v[216:219], 0
	v_mfma_f32_16x16x32_bf16 v[52:55], v[166:169], v[196:199], v[52:55]
	v_mfma_f32_16x16x32_bf16 v[48:51], v[180:183], v[196:199], v[48:51]
	v_mfma_f32_16x16x32_bf16 v[36:39], v[166:169], v[204:207], v[36:39]
	v_mfma_f32_16x16x32_bf16 v[32:35], v[180:183], v[204:207], v[32:35]
	v_mfma_f32_16x16x32_bf16 v[20:23], v[166:169], v[212:215], v[20:23]
	v_mfma_f32_16x16x32_bf16 v[16:19], v[180:183], v[212:215], v[16:19]
	v_mfma_f32_16x16x32_bf16 v[4:7], v[166:169], v[220:223], v[4:7]
	v_mfma_f32_16x16x32_bf16 v[0:3], v[180:183], v[220:223], v[0:3]
	s_setprio 0
	s_barrier
	s_add_i32 s36, 0, 0x18000
	s_add_i32 s37, 0, 0x1c000
	v_add_u32_e32 v154, s36, v162
	v_add_u32_e32 v180, s37, v162
	ds_read_b128 v[132:135], v154
	ds_read_b128 v[146:149], v154 offset:1024
	ds_read_b128 v[150:153], v154 offset:2048
	ds_read_b128 v[154:157], v154 offset:3072
	ds_read_b128 v[158:161], v180
	ds_read_b128 v[166:169], v180 offset:1024
	ds_read_b128 v[170:173], v180 offset:2048
	ds_read_b128 v[180:183], v180 offset:3072
	s_add_u32 s34, s34, vcc_hi
	s_addc_u32 s35, s35, s61
	s_mov_b32 m0, s68
	ds_read_b128 v[192:195], v165 offset:32768
	ds_read_b128 v[196:199], v165 offset:33792
	ds_read_b128 v[200:203], v165 offset:34816
	ds_read_b128 v[204:207], v165 offset:35840
	ds_read_b128 v[208:211], v165 offset:36864
	ds_read_b128 v[212:215], v165 offset:37888
	ds_read_b128 v[216:219], v165 offset:38912
	ds_read_b128 v[220:223], v165 offset:39936
	global_load_lds_dwordx4 v224, s[34:35]
	s_mov_b32 m0, s69
	s_nop 0
	global_load_lds_dwordx4 v178, s[34:35]
	s_waitcnt vmcnt(8)
	s_waitcnt lgkmcnt(0)
	s_barrier
	s_setprio 1
	s_waitcnt lgkmcnt(0)
	v_mfma_f32_16x16x32_bf16 v[124:127], v[132:135], v[192:195], v[124:127]
	v_mfma_f32_16x16x32_bf16 v[120:123], v[150:153], v[192:195], v[120:123]
	v_mfma_f32_16x16x32_bf16 v[108:111], v[132:135], v[200:203], v[108:111]
	v_mfma_f32_16x16x32_bf16 v[104:107], v[150:153], v[200:203], v[104:107]
	v_mfma_f32_16x16x32_bf16 v[92:95], v[132:135], v[208:211], v[92:95]
	v_mfma_f32_16x16x32_bf16 v[88:91], v[150:153], v[208:211], v[88:91]
	v_mfma_f32_16x16x32_bf16 v[76:79], v[132:135], v[216:219], v[76:79]
	v_mfma_f32_16x16x32_bf16 v[72:75], v[150:153], v[216:219], v[72:75]
	v_mfma_f32_16x16x32_bf16 v[124:127], v[146:149], v[196:199], v[124:127]
	v_mfma_f32_16x16x32_bf16 v[120:123], v[154:157], v[196:199], v[120:123]
	v_mfma_f32_16x16x32_bf16 v[108:111], v[146:149], v[204:207], v[108:111]
	v_mfma_f32_16x16x32_bf16 v[104:107], v[154:157], v[204:207], v[104:107]
	v_mfma_f32_16x16x32_bf16 v[92:95], v[146:149], v[212:215], v[92:95]
	v_mfma_f32_16x16x32_bf16 v[88:91], v[154:157], v[212:215], v[88:91]
	v_mfma_f32_16x16x32_bf16 v[76:79], v[146:149], v[220:223], v[76:79]
	v_mfma_f32_16x16x32_bf16 v[72:75], v[154:157], v[220:223], v[72:75]
	s_setprio 0
	s_setprio 1
	v_mfma_f32_16x16x32_bf16 v[116:119], v[158:161], v[192:195], v[116:119]
	v_mfma_f32_16x16x32_bf16 v[112:115], v[170:173], v[192:195], v[112:115]
	v_mfma_f32_16x16x32_bf16 v[100:103], v[158:161], v[200:203], v[100:103]
	v_mfma_f32_16x16x32_bf16 v[96:99], v[170:173], v[200:203], v[96:99]
	v_mfma_f32_16x16x32_bf16 v[84:87], v[158:161], v[208:211], v[84:87]
	v_mfma_f32_16x16x32_bf16 v[80:83], v[170:173], v[208:211], v[80:83]
	v_mfma_f32_16x16x32_bf16 v[68:71], v[158:161], v[216:219], v[68:71]
	v_mfma_f32_16x16x32_bf16 v[64:67], v[170:173], v[216:219], v[64:67]
	v_mfma_f32_16x16x32_bf16 v[116:119], v[166:169], v[196:199], v[116:119]
	v_mfma_f32_16x16x32_bf16 v[112:115], v[180:183], v[196:199], v[112:115]
	v_mfma_f32_16x16x32_bf16 v[100:103], v[166:169], v[204:207], v[100:103]
	v_mfma_f32_16x16x32_bf16 v[96:99], v[180:183], v[204:207], v[96:99]
	v_mfma_f32_16x16x32_bf16 v[84:87], v[166:169], v[212:215], v[84:87]
	v_mfma_f32_16x16x32_bf16 v[80:83], v[180:183], v[212:215], v[80:83]
	v_mfma_f32_16x16x32_bf16 v[68:71], v[166:169], v[220:223], v[68:71]
	v_mfma_f32_16x16x32_bf16 v[64:67], v[180:183], v[220:223], v[64:67]
	s_setprio 0
	s_barrier
; #define PG8_STAGE(bufoff, gbase, v0, dv) do { _Pragma("unroll") for (int _i = 0; _i < 2; ++_i) \
;         __builtin_amdgcn_global_load_lds((const unsigned*)((const char*)(gbase) + ((v0) + (unsigned)_i * (dv))), (PG8_LAS unsigned*)(lds + (bufoff) + ldsw + _i * 8192), 16, 0, 0); } while (0)
; #define PG8_LDA(dst, b, h) do { _Pragma("unroll") for (int m = 0; m < 4; ++m) _Pragma("unroll") for (int k = 0; k < 2; ++k) dst[m][k] = *(const PG8_LAS bf16x8*)(lds + PG8_SA(b, h) + aoff + m * 2048 + k * 1024); } while (0)
; #define PG8_LDB(dst, b, h) do { _Pragma("unroll") for (int n = 0; n < 2; ++n) _Pragma("unroll") for (int k = 0; k < 2; ++k) dst[n][k] = *(const PG8_LAS bf16x8*)(lds + PG8_SB(b, h) + boff + n * 2048 + k * 1024); } while (0)
; #define PG8_MMA(ai, bj, At, Bt) do { __builtin_amdgcn_s_setprio(1); _Pragma("unroll") for (int m = 0; m < 4; ++m) _Pragma("unroll") for (int n = 0; n < 2; ++n) _Pragma("unroll") for (int k = 0; k < 2; ++k) \
;         acc[ai][bj][m][n] = __builtin_amdgcn_mfma_f32_16x16x32_bf16(Bt[n][k], At[m][k], acc[ai][bj][m][n], 0, 0, 0); __builtin_amdgcn_s_setprio(0); } while (0)
; #define PG8_WAIT_V(n) asm volatile("s_waitcnt vmcnt(" #n ")" ::: "memory")
; #define PG8_WAIT_L(n) asm volatile("s_waitcnt lgkmcnt(" #n ")" ::: "memory")
; #define PG8_BAR __builtin_amdgcn_s_barrier()
; #define PG8_SCHED __builtin_amdgcn_sched_barrier(0)
; template <class Epi, class Sched, bool MERGE>
; __device__ __forceinline__ void gemm_stream(PG8_LAS unsigned char* lds, const Sched& S, const Epi& E) {
;     ...
;             PG8_LDB(B0, 0, 0); PG8_LDB(B1, 0, 1); PG8_SCHED; PG8_LDA(At, 0, 0); PG8_STAGE(PG8_SA(1, 1), a1 + chs, cvA, cdv);
;             PG8_WAIT_V(8); PG8_WAIT_L(0); PG8_BAR; PG8_MMA(0, 0, At, B0); PG8_MMA(0, 1, At, B1); PG8_BAR; PG8_SCHED;
;     ...
;             PG8_LDA(At, 1, 1); PG8_STAGE(PG8_SB(1, 0), b3, vB2, dv2); PG8_STAGE(PG8_SB(1, 1), b3 + hs2, vB2, dv2); PG8_STAGE(PG8_SA(1, 0), a3, vA2, dv2);
;             PG8_WAIT_V(8); PG8_WAIT_L(0); PG8_BAR; PG8_MMA(1, 0, At, B0); PG8_MMA(1, 1, At, B1); PG8_BAR; PG8_SCHED;
	s_add_i32 s34, s36, s65
	v_lshl_add_u64 v[224:225], v[230:231], 0, s[48:49]
	s_mov_b32 m0, s34
	ds_read_b128 v[192:195], v165 offset:49152
	ds_read_b128 v[196:199], v165 offset:50176
	ds_read_b128 v[200:203], v165 offset:51200
	ds_read_b128 v[204:207], v165 offset:52224
	ds_read_b128 v[208:211], v165 offset:53248
	ds_read_b128 v[212:215], v165 offset:54272
	ds_read_b128 v[216:219], v165 offset:55296
	ds_read_b128 v[220:223], v165 offset:56320
	global_load_lds_dwordx4 v[224:225], off
	v_lshl_add_u64 v[224:225], v[232:233], 0, s[48:49]
	s_add_i32 m0, s34, 0x2000
	s_add_i32 s34, s37, s65
	global_load_lds_dwordx4 v[224:225], off
	v_lshl_add_u64 v[224:225], v[234:235], 0, s[48:49]
	s_mov_b32 m0, s34
	v_lshl_add_u64 v[174:175], v[174:175], 0, s[48:49]
	global_load_lds_dwordx4 v[224:225], off
	s_add_i32 m0, s34, 0x2000
	s_nop 0
	global_load_lds_dwordx4 v[174:175], off
	v_lshl_add_u64 v[174:175], v[236:237], 0, s[48:49]
	s_mov_b32 m0, s71
	s_nop 0
	global_load_lds_dwordx4 v[174:175], off
	v_lshl_add_u64 v[174:175], v[238:239], 0, s[48:49]
	s_mov_b32 m0, s74
	s_nop 0
	global_load_lds_dwordx4 v[174:175], off
	s_waitcnt vmcnt(8)
	s_waitcnt lgkmcnt(0)
	s_barrier
	s_setprio 1
	s_waitcnt lgkmcnt(0)
	v_mfma_f32_16x16x32_bf16 v[60:63], v[132:135], v[192:195], v[60:63]
	v_mfma_f32_16x16x32_bf16 v[56:59], v[150:153], v[192:195], v[56:59]
	v_mfma_f32_16x16x32_bf16 v[44:47], v[132:135], v[200:203], v[44:47]
	v_mfma_f32_16x16x32_bf16 v[40:43], v[150:153], v[200:203], v[40:43]
	v_mfma_f32_16x16x32_bf16 v[28:31], v[132:135], v[208:211], v[28:31]
	v_mfma_f32_16x16x32_bf16 v[24:27], v[150:153], v[208:211], v[24:27]
	v_mfma_f32_16x16x32_bf16 v[12:15], v[132:135], v[216:219], v[12:15]
	v_mfma_f32_16x16x32_bf16 v[8:11], v[150:153], v[216:219], v[8:11]
	v_mfma_f32_16x16x32_bf16 v[60:63], v[146:149], v[196:199], v[60:63]
	v_mfma_f32_16x16x32_bf16 v[56:59], v[154:157], v[196:199], v[56:59]
	v_mfma_f32_16x16x32_bf16 v[44:47], v[146:149], v[204:207], v[44:47]
	v_mfma_f32_16x16x32_bf16 v[40:43], v[154:157], v[204:207], v[40:43]
	v_mfma_f32_16x16x32_bf16 v[28:31], v[146:149], v[212:215], v[28:31]
	v_mfma_f32_16x16x32_bf16 v[24:27], v[154:157], v[212:215], v[24:27]
	v_mfma_f32_16x16x32_bf16 v[12:15], v[146:149], v[220:223], v[12:15]
	v_mfma_f32_16x16x32_bf16 v[8:11], v[154:157], v[220:223], v[8:11]
	s_setprio 0
	s_setprio 1
	v_mfma_f32_16x16x32_bf16 v[52:55], v[158:161], v[192:195], v[52:55]
	v_mfma_f32_16x16x32_bf16 v[48:51], v[170:173], v[192:195], v[48:51]
	v_mfma_f32_16x16x32_bf16 v[36:39], v[158:161], v[200:203], v[36:39]
	v_mfma_f32_16x16x32_bf16 v[32:35], v[170:173], v[200:203], v[32:35]
	v_mfma_f32_16x16x32_bf16 v[20:23], v[158:161], v[208:211], v[20:23]
	v_mfma_f32_16x16x32_bf16 v[16:19], v[170:173], v[208:211], v[16:19]
	v_mfma_f32_16x16x32_bf16 v[4:7], v[158:161], v[216:219], v[4:7]
	v_mfma_f32_16x16x32_bf16 v[0:3], v[170:173], v[216:219], v[0:3]
	v_mfma_f32_16x16x32_bf16 v[52:55], v[166:169], v[196:199], v[52:55]
	v_mfma_f32_16x16x32_bf16 v[48:51], v[180:183], v[196:199], v[48:51]
	v_mfma_f32_16x16x32_bf16 v[36:39], v[166:169], v[204:207], v[36:39]
	v_mfma_f32_16x16x32_bf16 v[32:35], v[180:183], v[204:207], v[32:35]
	v_mfma_f32_16x16x32_bf16 v[20:23], v[166:169], v[212:215], v[20:23]
	v_mfma_f32_16x16x32_bf16 v[16:19], v[180:183], v[212:215], v[16:19]
	v_mfma_f32_16x16x32_bf16 v[4:7], v[166:169], v[220:223], v[4:7]
	v_mfma_f32_16x16x32_bf16 v[0:3], v[180:183], v[220:223], v[0:3]
	s_setprio 0
	s_barrier
	s_add_u32 s6, s6, 0x100
	s_addc_u32 s7, s7, 0
	s_add_u32 s73, s73, 0x100
	s_addc_u32 s94, s94, 0
	s_cmp_ge_i32 vcc_lo, s27
	s_cbranch_scc1 .LBB0_238
.LBB0_237:
	s_mov_b32 s96, 0x10000
	v_add_u32_e32 v154, s96, v162
	v_add_u32_e32 v175, 0x14000, v162
	ds_read_b128 v[132:135], v154
	ds_read_b128 v[146:149], v154 offset:1024
	ds_read_b128 v[150:153], v154 offset:2048
	ds_read_b128 v[154:157], v154 offset:3072
	ds_read_b128 v[158:161], v175
	ds_read_b128 v[166:169], v175 offset:1024
	ds_read_b128 v[170:173], v175 offset:2048
	ds_read_b128 v[180:183], v175 offset:3072
	s_cmp_eq_u32 s59, vcc_lo
	s_cselect_b64 s[36:37], -1, 0
	s_add_i32 vcc_lo, vcc_lo, 2
	s_add_u32 s50, s6, 0x80
	s_addc_u32 s51, s7, 0
	s_and_b64 s[34:35], s[36:37], exec
	s_cselect_b32 s35, s23, s51
	s_cselect_b32 s34, s22, s50
	s_cselect_b32 s58, s47, s46
	s_cselect_b32 s61, s29, s31
	s_cselect_b32 vcc_hi, s28, s30
	s_add_i32 s96, 0, 0x10000
	v_mad_u64_u32 v[174:175], s[50:51], s58, v139, v[136:137]
	s_and_b64 s[36:37], s[36:37], exec
	v_mad_u64_u32 v[224:225], s[50:51], s58, v137, v[136:137]
	s_cselect_b32 s37, s25, s94
	s_cselect_b32 s36, s24, s73
	s_add_i32 s50, 0, 0x14000
	v_lshl_add_u64 v[230:231], s[6:7], 0, v[128:129]
	s_add_i32 m0, s66, 0xc000
	ds_read_b128 v[192:195], v165
	ds_read_b128 v[196:199], v165 offset:1024
	ds_read_b128 v[200:203], v165 offset:2048
	ds_read_b128 v[204:207], v165 offset:3072
	ds_read_b128 v[208:211], v165 offset:4096
	ds_read_b128 v[212:215], v165 offset:5120
	ds_read_b128 v[216:219], v165 offset:6144
	ds_read_b128 v[220:223], v165 offset:7168
	global_load_lds_dwordx4 v[230:231], off
	v_lshl_add_u64 v[230:231], s[6:7], 0, v[130:131]
	s_add_i32 m0, s66, 0xe000
	s_nop 0
	global_load_lds_dwordx4 v[230:231], off
	s_waitcnt vmcnt(8)
	s_waitcnt lgkmcnt(0)
	s_barrier
; #define PG8_STAGE(bufoff, gbase, v0, dv) do { _Pragma("unroll") for (int _i = 0; _i < 2; ++_i) \
;         __builtin_amdgcn_global_load_lds((const unsigned*)((const char*)(gbase) + ((v0) + (unsigned)_i * (dv))), (PG8_LAS unsigned*)(lds + (bufoff) + ldsw + _i * 8192), 16, 0, 0); } while (0)
; #define PG8_LDA(dst, b, h) do { _Pragma("unroll") for (int m = 0; m < 4; ++m) _Pragma("unroll") for (int k = 0; k < 2; ++k) dst[m][k] = *(const PG8_LAS bf16x8*)(lds + PG8_SA(b, h) + aoff + m * 2048 + k * 1024); } while (0)
; #define PG8_LDB(dst, b, h) do { _Pragma("unroll") for (int n = 0; n < 2; ++n) _Pragma("unroll") for (int k = 0; k < 2; ++k) dst[n][k] = *(const PG8_LAS bf16x8*)(lds + PG8_SB(b, h) + boff + n * 2048 + k * 1024); } while (0)
; #define PG8_MMA(ai, bj, At, Bt) do { __builtin_amdgcn_s_setprio(1); _Pragma("unroll") for (int m = 0; m < 4; ++m) _Pragma("unroll") for (int n = 0; n < 2; ++n) _Pragma("unroll") for (int k = 0; k < 2; ++k) \
;         acc[ai][bj][m][n] = __builtin_amdgcn_mfma_f32_16x16x32_bf16(Bt[n][k], At[m][k], acc[ai][bj][m][n], 0, 0, 0); __builtin_amdgcn_s_setprio(0); } while (0)
; #define PG8_WAIT_V(n) asm volatile("s_waitcnt vmcnt(" #n ")" ::: "memory")
; #define PG8_WAIT_L(n) asm volatile("s_waitcnt lgkmcnt(" #n ")" ::: "memory")
; #define PG8_BAR __builtin_amdgcn_s_barrier()
; #define PG8_SCHED __builtin_amdgcn_sched_barrier(0)
; template <class Epi, class Sched, bool MERGE>
; __device__ __forceinline__ void gemm_stream(PG8_LAS unsigned char* lds, const Sched& S, const Epi& E) {
;     ...
;             PG8_LDB(B0, 0, 0); PG8_LDB(B1, 0, 1); PG8_SCHED; PG8_LDA(At, 0, 0); PG8_STAGE(PG8_SA(1, 1), a1 + chs, cvA, cdv);
;             PG8_WAIT_V(8); PG8_WAIT_L(0); PG8_BAR; PG8_MMA(0, 0, At, B0); PG8_MMA(0, 1, At, B1); PG8_BAR; PG8_SCHED;
;             PG8_LDA(At, 0, 1); PG8_STAGE(PG8_SB(0, 0), b2, vB2, dv2); PG8_STAGE(PG8_SB(0, 1), b2 + hs2, vB2, dv2); PG8_STAGE(PG8_SA(0, 0), a2, vA2, dv2);
;             PG8_WAIT_V(8); PG8_WAIT_L(0); PG8_BAR; PG8_MMA(1, 0, At, B0); PG8_MMA(1, 1, At, B1); PG8_BAR; PG8_SCHED;
	s_setprio 1
	s_waitcnt lgkmcnt(0)
	v_mfma_f32_16x16x32_bf16 v[124:127], v[132:135], v[192:195], v[124:127]
	v_mfma_f32_16x16x32_bf16 v[120:123], v[150:153], v[192:195], v[120:123]
	v_mfma_f32_16x16x32_bf16 v[108:111], v[132:135], v[200:203], v[108:111]
	v_mfma_f32_16x16x32_bf16 v[104:107], v[150:153], v[200:203], v[104:107]
	v_mfma_f32_16x16x32_bf16 v[92:95], v[132:135], v[208:211], v[92:95]
	v_mfma_f32_16x16x32_bf16 v[88:91], v[150:153], v[208:211], v[88:91]
	v_mfma_f32_16x16x32_bf16 v[76:79], v[132:135], v[216:219], v[76:79]
	v_mfma_f32_16x16x32_bf16 v[72:75], v[150:153], v[216:219], v[72:75]
	v_mfma_f32_16x16x32_bf16 v[124:127], v[146:149], v[196:199], v[124:127]
	v_mfma_f32_16x16x32_bf16 v[120:123], v[154:157], v[196:199], v[120:123]
	v_mfma_f32_16x16x32_bf16 v[108:111], v[146:149], v[204:207], v[108:111]
	v_mfma_f32_16x16x32_bf16 v[104:107], v[154:157], v[204:207], v[104:107]
	v_mfma_f32_16x16x32_bf16 v[92:95], v[146:149], v[212:215], v[92:95]
	v_mfma_f32_16x16x32_bf16 v[88:91], v[154:157], v[212:215], v[88:91]
	v_mfma_f32_16x16x32_bf16 v[76:79], v[146:149], v[220:223], v[76:79]
	v_mfma_f32_16x16x32_bf16 v[72:75], v[154:157], v[220:223], v[72:75]
	s_setprio 0
	s_setprio 1
	v_mfma_f32_16x16x32_bf16 v[116:119], v[158:161], v[192:195], v[116:119]
	v_mfma_f32_16x16x32_bf16 v[112:115], v[170:173], v[192:195], v[112:115]
	v_mfma_f32_16x16x32_bf16 v[100:103], v[158:161], v[200:203], v[100:103]
	v_mfma_f32_16x16x32_bf16 v[96:99], v[170:173], v[200:203], v[96:99]
	v_mfma_f32_16x16x32_bf16 v[84:87], v[158:161], v[208:211], v[84:87]
	v_mfma_f32_16x16x32_bf16 v[80:83], v[170:173], v[208:211], v[80:83]
	v_mfma_f32_16x16x32_bf16 v[68:71], v[158:161], v[216:219], v[68:71]
	v_mfma_f32_16x16x32_bf16 v[64:67], v[170:173], v[216:219], v[64:67]
	v_mfma_f32_16x16x32_bf16 v[116:119], v[166:169], v[196:199], v[116:119]
	v_mfma_f32_16x16x32_bf16 v[112:115], v[180:183], v[196:199], v[112:115]
	v_mfma_f32_16x16x32_bf16 v[100:103], v[166:169], v[204:207], v[100:103]
	v_mfma_f32_16x16x32_bf16 v[96:99], v[180:183], v[204:207], v[96:99]
	v_mfma_f32_16x16x32_bf16 v[84:87], v[166:169], v[212:215], v[84:87]
	v_mfma_f32_16x16x32_bf16 v[80:83], v[180:183], v[212:215], v[80:83]
	v_mfma_f32_16x16x32_bf16 v[68:71], v[166:169], v[220:223], v[68:71]
	v_mfma_f32_16x16x32_bf16 v[64:67], v[180:183], v[220:223], v[64:67]
	s_setprio 0
	s_barrier
	s_lshl_b32 s51, s58, 6
	s_add_i32 s58, s96, s65
	s_mov_b32 m0, s58
	ds_read_b128 v[192:195], v165 offset:16384
	ds_read_b128 v[196:199], v165 offset:17408
	ds_read_b128 v[200:203], v165 offset:18432
	ds_read_b128 v[204:207], v165 offset:19456
	ds_read_b128 v[208:211], v165 offset:20480
	ds_read_b128 v[212:215], v165 offset:21504
	ds_read_b128 v[216:219], v165 offset:22528
	ds_read_b128 v[220:223], v165 offset:23552
	v_mov_b32_e32 v175, v179
	global_load_lds_dwordx4 v174, s[36:37]
	v_add_u32_e32 v178, s51, v174
	s_add_i32 m0, s58, 0x2000
	v_lshl_add_u64 v[230:231], s[36:37], 0, v[174:175]
	v_lshl_add_u64 v[232:233], s[36:37], 0, v[178:179]
	global_load_lds_dwordx4 v178, s[36:37]
	s_add_u32 s36, s36, vcc_hi
	s_addc_u32 s37, s37, s61
	s_add_i32 s50, s50, s65
	s_mov_b32 m0, s50
	v_lshl_add_u64 v[234:235], s[36:37], 0, v[174:175]
	global_load_lds_dwordx4 v174, s[36:37]
	s_add_i32 m0, s50, 0x2000
	v_lshl_add_u64 v[174:175], s[36:37], 0, v[178:179]
	global_load_lds_dwordx4 v178, s[36:37]
	s_mov_b32 m0, s66
	v_add_u32_e32 v178, s51, v224
	global_load_lds_dwordx4 v224, s[34:35]
	s_mov_b32 m0, s67
	v_mov_b32_e32 v225, v179
	global_load_lds_dwordx4 v178, s[34:35]
	s_waitcnt vmcnt(8)
	s_waitcnt lgkmcnt(0)
	v_lshl_add_u64 v[236:237], s[34:35], 0, v[224:225]
	v_lshl_add_u64 v[238:239], s[34:35], 0, v[178:179]
	s_barrier
	s_setprio 1
	s_waitcnt lgkmcnt(0)
	v_mfma_f32_16x16x32_bf16 v[60:63], v[132:135], v[192:195], v[60:63]
	v_mfma_f32_16x16x32_bf16 v[56:59], v[150:153], v[192:195], v[56:59]
	v_mfma_f32_16x16x32_bf16 v[44:47], v[132:135], v[200:203], v[44:47]
	v_mfma_f32_16x16x32_bf16 v[40:43], v[150:153], v[200:203], v[40:43]
	v_mfma_f32_16x16x32_bf16 v[28:31], v[132:135], v[208:211], v[28:31]
	v_mfma_f32_16x16x32_bf16 v[24:27], v[150:153], v[208:211], v[24:27]
	v_mfma_f32_16x16x32_bf16 v[12:15], v[132:135], v[216:219], v[12:15]
	v_mfma_f32_16x16x32_bf16 v[8:11], v[150:153], v[216:219], v[8:11]
	v_mfma_f32_16x16x32_bf16 v[60:63], v[146:149], v[196:199], v[60:63]
	v_mfma_f32_16x16x32_bf16 v[56:59], v[154:157], v[196:199], v[56:59]
	v_mfma_f32_16x16x32_bf16 v[44:47], v[146:149], v[204:207], v[44:47]
	v_mfma_f32_16x16x32_bf16 v[40:43], v[154:157], v[204:207], v[40:43]
	v_mfma_f32_16x16x32_bf16 v[28:31], v[146:149], v[212:215], v[28:31]
	v_mfma_f32_16x16x32_bf16 v[24:27], v[154:157], v[212:215], v[24:27]
	v_mfma_f32_16x16x32_bf16 v[12:15], v[146:149], v[220:223], v[12:15]
	v_mfma_f32_16x16x32_bf16 v[8:11], v[154:157], v[220:223], v[8:11]
	s_setprio 0
	s_setprio 1
	v_mfma_f32_16x16x32_bf16 v[52:55], v[158:161], v[192:195], v[52:55]
	v_mfma_f32_16x16x32_bf16 v[48:51], v[170:173], v[192:195], v[48:51]
	v_mfma_f32_16x16x32_bf16 v[36:39], v[158:161], v[200:203], v[36:39]
	v_mfma_f32_16x16x32_bf16 v[32:35], v[170:173], v[200:203], v[32:35]
	v_mfma_f32_16x16x32_bf16 v[20:23], v[158:161], v[208:211], v[20:23]
	v_mfma_f32_16x16x32_bf16 v[16:19], v[170:173], v[208:211], v[16:19]
	v_mfma_f32_16x16x32_bf16 v[4:7], v[158:161], v[216:219], v[4:7]
	v_mfma_f32_16x16x32_bf16 v[0:3], v[170:173], v[216:219], v[0:3]
	v_mfma_f32_16x16x32_bf16 v[52:55], v[166:169], v[196:199], v[52:55]
	v_mfma_f32_16x16x32_bf16 v[48:51], v[180:183], v[196:199], v[48:51]
	v_mfma_f32_16x16x32_bf16 v[36:39], v[166:169], v[204:207], v[36:39]
	v_mfma_f32_16x16x32_bf16 v[32:35], v[180:183], v[204:207], v[32:35]
	v_mfma_f32_16x16x32_bf16 v[20:23], v[166:169], v[212:215], v[20:23]
	v_mfma_f32_16x16x32_bf16 v[16:19], v[180:183], v[212:215], v[16:19]
	v_mfma_f32_16x16x32_bf16 v[4:7], v[166:169], v[220:223], v[4:7]
	v_mfma_f32_16x16x32_bf16 v[0:3], v[180:183], v[220:223], v[0:3]
	s_setprio 0
	s_barrier
; #define PG8_STAGE(bufoff, gbase, v0, dv) do { _Pragma("unroll") for (int _i = 0; _i < 2; ++_i) \
;         __builtin_amdgcn_global_load_lds((const unsigned*)((const char*)(gbase) + ((v0) + (unsigned)_i * (dv))), (PG8_LAS unsigned*)(lds + (bufoff) + ldsw + _i * 8192), 16, 0, 0); } while (0)
; #define PG8_LDA(dst, b, h) do { _Pragma("unroll") for (int m = 0; m < 4; ++m) _Pragma("unroll") for (int k = 0; k < 2; ++k) dst[m][k] = *(const PG8_LAS bf16x8*)(lds + PG8_SA(b, h) + aoff + m * 2048 + k * 1024); } while (0)
; #define PG8_LDB(dst, b, h) do { _Pragma("unroll") for (int n = 0; n < 2; ++n) _Pragma("unroll") for (int k = 0; k < 2; ++k) dst[n][k] = *(const PG8_LAS bf16x8*)(lds + PG8_SB(b, h) + boff + n * 2048 + k * 1024); } while (0)
; #define PG8_MMA(ai, bj, At, Bt) do { __builtin_amdgcn_s_setprio(1); _Pragma("unroll") for (int m = 0; m < 4; ++m) _Pragma("unroll") for (int n = 0; n < 2; ++n) _Pragma("unroll") for (int k = 0; k < 2; ++k) \
;         acc[ai][bj][m][n] = __builtin_amdgcn_mfma_f32_16x16x32_bf16(Bt[n][k], At[m][k], acc[ai][bj][m][n], 0, 0, 0); __builtin_amdgcn_s_setprio(0); } while (0)
; #define PG8_WAIT_V(n) asm volatile("s_waitcnt vmcnt(" #n ")" ::: "memory")
; #define PG8_WAIT_L(n) asm volatile("s_waitcnt lgkmcnt(" #n ")" ::: "memory")
; #define PG8_BAR __builtin_amdgcn_s_barrier()
; #define PG8_SCHED __builtin_amdgcn_sched_barrier(0)
; template <class Epi, class Sched, bool MERGE>
; __device__ __forceinline__ void gemm_stream(PG8_LAS unsigned char* lds, const Sched& S, const Epi& E) {
;     ...
;             PG8_LDB(B0, 1, 0); PG8_LDB(B1, 1, 1); PG8_SCHED; PG8_LDA(At, 1, 0); PG8_STAGE(PG8_SA(0, 1), a2 + hs2, vA2, dv2);
;             PG8_WAIT_V(8); PG8_WAIT_L(0); PG8_BAR; PG8_MMA(0, 0, At, B0); PG8_MMA(0, 1, At, B1); PG8_BAR; PG8_SCHED;
;             PG8_LDA(At, 1, 1); PG8_STAGE(PG8_SB(1, 0), b3, vB2, dv2); PG8_STAGE(PG8_SB(1, 1), b3 + hs2, vB2, dv2); PG8_STAGE(PG8_SA(1, 0), a3, vA2, dv2);
;             PG8_WAIT_V(8); PG8_WAIT_L(0); PG8_BAR; PG8_MMA(1, 0, At, B0); PG8_MMA(1, 1, At, B1); PG8_BAR; PG8_SCHED;
;         }
	s_add_i32 s36, 0, 0x18000
	s_add_i32 s37, 0, 0x1c000
	v_add_u32_e32 v154, s36, v162
	v_add_u32_e32 v180, s37, v162
	ds_read_b128 v[132:135], v154
	ds_read_b128 v[146:149], v154 offset:1024
	ds_read_b128 v[150:153], v154 offset:2048
	ds_read_b128 v[154:157], v154 offset:3072
	ds_read_b128 v[158:161], v180
	ds_read_b128 v[166:169], v180 offset:1024
	ds_read_b128 v[170:173], v180 offset:2048
	ds_read_b128 v[180:183], v180 offset:3072
	s_add_u32 s34, s34, vcc_hi
	s_addc_u32 s35, s35, s61
	s_mov_b32 m0, s68
	ds_read_b128 v[192:195], v165 offset:32768
	ds_read_b128 v[196:199], v165 offset:33792
	ds_read_b128 v[200:203], v165 offset:34816
	ds_read_b128 v[204:207], v165 offset:35840
	ds_read_b128 v[208:211], v165 offset:36864
	ds_read_b128 v[212:215], v165 offset:37888
	ds_read_b128 v[216:219], v165 offset:38912
	ds_read_b128 v[220:223], v165 offset:39936
	global_load_lds_dwordx4 v224, s[34:35]
	s_mov_b32 m0, s69
	s_nop 0
	global_load_lds_dwordx4 v178, s[34:35]
	s_waitcnt vmcnt(8)
	s_waitcnt lgkmcnt(0)
	s_barrier
	s_setprio 1
	s_waitcnt lgkmcnt(0)
	v_mfma_f32_16x16x32_bf16 v[124:127], v[132:135], v[192:195], v[124:127]
	v_mfma_f32_16x16x32_bf16 v[120:123], v[150:153], v[192:195], v[120:123]
	v_mfma_f32_16x16x32_bf16 v[108:111], v[132:135], v[200:203], v[108:111]
	v_mfma_f32_16x16x32_bf16 v[104:107], v[150:153], v[200:203], v[104:107]
	v_mfma_f32_16x16x32_bf16 v[92:95], v[132:135], v[208:211], v[92:95]
	v_mfma_f32_16x16x32_bf16 v[88:91], v[150:153], v[208:211], v[88:91]
	v_mfma_f32_16x16x32_bf16 v[76:79], v[132:135], v[216:219], v[76:79]
	v_mfma_f32_16x16x32_bf16 v[72:75], v[150:153], v[216:219], v[72:75]
	v_mfma_f32_16x16x32_bf16 v[124:127], v[146:149], v[196:199], v[124:127]
	v_mfma_f32_16x16x32_bf16 v[120:123], v[154:157], v[196:199], v[120:123]
	v_mfma_f32_16x16x32_bf16 v[108:111], v[146:149], v[204:207], v[108:111]
	v_mfma_f32_16x16x32_bf16 v[104:107], v[154:157], v[204:207], v[104:107]
	v_mfma_f32_16x16x32_bf16 v[92:95], v[146:149], v[212:215], v[92:95]
	v_mfma_f32_16x16x32_bf16 v[88:91], v[154:157], v[212:215], v[88:91]
	v_mfma_f32_16x16x32_bf16 v[76:79], v[146:149], v[220:223], v[76:79]
	v_mfma_f32_16x16x32_bf16 v[72:75], v[154:157], v[220:223], v[72:75]
	s_setprio 0
	s_setprio 1
	v_mfma_f32_16x16x32_bf16 v[116:119], v[158:161], v[192:195], v[116:119]
	v_mfma_f32_16x16x32_bf16 v[112:115], v[170:173], v[192:195], v[112:115]
	v_mfma_f32_16x16x32_bf16 v[100:103], v[158:161], v[200:203], v[100:103]
	v_mfma_f32_16x16x32_bf16 v[96:99], v[170:173], v[200:203], v[96:99]
	v_mfma_f32_16x16x32_bf16 v[84:87], v[158:161], v[208:211], v[84:87]
	v_mfma_f32_16x16x32_bf16 v[80:83], v[170:173], v[208:211], v[80:83]
	v_mfma_f32_16x16x32_bf16 v[68:71], v[158:161], v[216:219], v[68:71]
	v_mfma_f32_16x16x32_bf16 v[64:67], v[170:173], v[216:219], v[64:67]
	v_mfma_f32_16x16x32_bf16 v[116:119], v[166:169], v[196:199], v[116:119]
	v_mfma_f32_16x16x32_bf16 v[112:115], v[180:183], v[196:199], v[112:115]
	v_mfma_f32_16x16x32_bf16 v[100:103], v[166:169], v[204:207], v[100:103]
	v_mfma_f32_16x16x32_bf16 v[96:99], v[180:183], v[204:207], v[96:99]
	v_mfma_f32_16x16x32_bf16 v[84:87], v[166:169], v[212:215], v[84:87]
	v_mfma_f32_16x16x32_bf16 v[80:83], v[180:183], v[212:215], v[80:83]
	v_mfma_f32_16x16x32_bf16 v[68:71], v[166:169], v[220:223], v[68:71]
	v_mfma_f32_16x16x32_bf16 v[64:67], v[180:183], v[220:223], v[64:67]
	s_setprio 0
	s_barrier
	s_add_i32 s34, s36, s65
	v_lshl_add_u64 v[224:225], v[230:231], 0, s[48:49]
	s_mov_b32 m0, s34
	ds_read_b128 v[192:195], v165 offset:49152
	ds_read_b128 v[196:199], v165 offset:50176
	ds_read_b128 v[200:203], v165 offset:51200
	ds_read_b128 v[204:207], v165 offset:52224
	ds_read_b128 v[208:211], v165 offset:53248
	ds_read_b128 v[212:215], v165 offset:54272
	ds_read_b128 v[216:219], v165 offset:55296
	ds_read_b128 v[220:223], v165 offset:56320
	global_load_lds_dwordx4 v[224:225], off
	v_lshl_add_u64 v[224:225], v[232:233], 0, s[48:49]
	s_add_i32 m0, s34, 0x2000
	s_add_i32 s34, s37, s65
	global_load_lds_dwordx4 v[224:225], off
	v_lshl_add_u64 v[224:225], v[234:235], 0, s[48:49]
	s_mov_b32 m0, s34
	v_lshl_add_u64 v[174:175], v[174:175], 0, s[48:49]
	global_load_lds_dwordx4 v[224:225], off
	s_add_i32 m0, s34, 0x2000
	s_nop 0
	global_load_lds_dwordx4 v[174:175], off
	v_lshl_add_u64 v[174:175], v[236:237], 0, s[48:49]
	s_mov_b32 m0, s71
	s_nop 0
	global_load_lds_dwordx4 v[174:175], off
	v_lshl_add_u64 v[174:175], v[238:239], 0, s[48:49]
	s_mov_b32 m0, s74
	s_nop 0
	global_load_lds_dwordx4 v[174:175], off
	s_waitcnt vmcnt(8)
	s_waitcnt lgkmcnt(0)
	s_barrier
	s_setprio 1
	s_waitcnt lgkmcnt(0)
	v_mfma_f32_16x16x32_bf16 v[60:63], v[132:135], v[192:195], v[60:63]
	v_mfma_f32_16x16x32_bf16 v[56:59], v[150:153], v[192:195], v[56:59]
	v_mfma_f32_16x16x32_bf16 v[44:47], v[132:135], v[200:203], v[44:47]
	v_mfma_f32_16x16x32_bf16 v[40:43], v[150:153], v[200:203], v[40:43]
	v_mfma_f32_16x16x32_bf16 v[28:31], v[132:135], v[208:211], v[28:31]
	v_mfma_f32_16x16x32_bf16 v[24:27], v[150:153], v[208:211], v[24:27]
	v_mfma_f32_16x16x32_bf16 v[12:15], v[132:135], v[216:219], v[12:15]
	v_mfma_f32_16x16x32_bf16 v[8:11], v[150:153], v[216:219], v[8:11]
	v_mfma_f32_16x16x32_bf16 v[60:63], v[146:149], v[196:199], v[60:63]
	v_mfma_f32_16x16x32_bf16 v[56:59], v[154:157], v[196:199], v[56:59]
	v_mfma_f32_16x16x32_bf16 v[44:47], v[146:149], v[204:207], v[44:47]
	v_mfma_f32_16x16x32_bf16 v[40:43], v[154:157], v[204:207], v[40:43]
	v_mfma_f32_16x16x32_bf16 v[28:31], v[146:149], v[212:215], v[28:31]
	v_mfma_f32_16x16x32_bf16 v[24:27], v[154:157], v[212:215], v[24:27]
	v_mfma_f32_16x16x32_bf16 v[12:15], v[146:149], v[220:223], v[12:15]
	v_mfma_f32_16x16x32_bf16 v[8:11], v[154:157], v[220:223], v[8:11]
	s_setprio 0
	s_setprio 1
	v_mfma_f32_16x16x32_bf16 v[52:55], v[158:161], v[192:195], v[52:55]
	v_mfma_f32_16x16x32_bf16 v[48:51], v[170:173], v[192:195], v[48:51]
	v_mfma_f32_16x16x32_bf16 v[36:39], v[158:161], v[200:203], v[36:39]
	v_mfma_f32_16x16x32_bf16 v[32:35], v[170:173], v[200:203], v[32:35]
	v_mfma_f32_16x16x32_bf16 v[20:23], v[158:161], v[208:211], v[20:23]
	v_mfma_f32_16x16x32_bf16 v[16:19], v[170:173], v[208:211], v[16:19]
	v_mfma_f32_16x16x32_bf16 v[4:7], v[158:161], v[216:219], v[4:7]
	v_mfma_f32_16x16x32_bf16 v[0:3], v[170:173], v[216:219], v[0:3]
	v_mfma_f32_16x16x32_bf16 v[52:55], v[166:169], v[196:199], v[52:55]
	v_mfma_f32_16x16x32_bf16 v[48:51], v[180:183], v[196:199], v[48:51]
	v_mfma_f32_16x16x32_bf16 v[36:39], v[166:169], v[204:207], v[36:39]
	v_mfma_f32_16x16x32_bf16 v[32:35], v[180:183], v[204:207], v[32:35]
	v_mfma_f32_16x16x32_bf16 v[20:23], v[166:169], v[212:215], v[20:23]
	v_mfma_f32_16x16x32_bf16 v[16:19], v[180:183], v[212:215], v[16:19]
	v_mfma_f32_16x16x32_bf16 v[4:7], v[166:169], v[220:223], v[4:7]
	v_mfma_f32_16x16x32_bf16 v[0:3], v[180:183], v[220:223], v[0:3]
	s_setprio 0
	s_barrier
	s_add_u32 s6, s6, 0x100
	s_addc_u32 s7, s7, 0
	s_add_u32 s73, s73, 0x100
	s_addc_u32 s94, s94, 0
	s_cmp_ge_i32 vcc_lo, s27
	s_cbranch_scc0 .LBB0_237
